# E2 + static s_setprio 1 for the attention waves (0-3) during the overlapped attention/selection phase
# speedup vs baseline: 1.0090x; 1.0090x over previous
.Lp5a_begin:
	s_setprio 1
	s_cmp_gt_i32 s43, 5
	s_cselect_b64 s[4:5], -1, 0
	s_cmp_lt_i32 s42, 6
	s_cselect_b64 s[0:1], -1, 0
	s_and_b64 s[0:1], s[0:1], s[4:5]
	s_andn2_b64 vcc, exec, s[0:1]
	s_cbranch_vccnz .Lp5a_exit
	v_readlane_b32 s0, v255, 0
	v_readlane_b32 s1, v255, 1
	s_cmpk_lg_i32 s44, 0x100
	s_mov_b64 s[10:11], 0
	s_waitcnt vmcnt(0)
	v_mbcnt_lo_u32_b32 v164, -1, 0
	v_mbcnt_hi_u32_b32 v164, -1, v164
	s_cbranch_scc1 .LBB0_2934
	s_add_i32 s0, 0, 0x20000
	v_mov_b32_e32 v0, s0
	ds_read_b32 v0, v0
	s_waitcnt lgkmcnt(0)
	v_cmp_ne_u32_e32 vcc, 32, v0
	s_cbranch_vccnz .LBB0_2934
	s_add_i32 s0, 0, 0x20004
	v_mov_b32_e32 v0, s0
	ds_read_b32 v0, v0
	s_waitcnt lgkmcnt(0)
	v_cmp_ne_u32_e32 vcc, 8, v0
	s_cbranch_vccnz .LBB0_2934
	s_add_i32 s0, 0, 0x2000c
	v_mov_b32_e32 v0, s0
	ds_read_b32 v0, v0
	s_waitcnt lgkmcnt(0)
	v_readfirstlane_b32 s0, v0
	s_cmp_lt_u32 s0, 8
	s_cselect_b64 s[10:11], -1, 0

.Lp5a_exit:
	s_setprio 0
	s_and_b64 vcc, exec, s[88:89]
	s_cbranch_vccnz .LBB0_4694
	s_mov_b32 s90, 1
	s_waitcnt lgkmcnt(0)
	s_barrier
	s_branch .LBB0_3029
